# P3b EpiMerge epilogue: gate loads batched (rolling 16 in flight) instead of one dependent load per vmcnt(0)
# speedup vs baseline: 1.0164x; 1.0164x over previous
.LBB0_608:
	v_lshl_add_u32 v144, s2, 8, v174
	v_lshl_or_b32 v2, s86, 8, v176
	s_lshl_b32 s62, s3, 11
	v_lshlrev_b32_e32 v145, 13, v144
	v_lshlrev_b32_e32 v148, 11, v144
	s_add_u32 s4, s36, s62
	s_addc_u32 s5, s37, 0
	v_lshl_add_u32 v145, v2, 1, v145
	v_lshl_add_u32 v148, v2, 1, v148
	s_cmp_eq_u32 s3, 3
	s_cselect_b64 s[64:65], -1, 0
	s_cbranch_scc1 .Lem_b3
	global_load_dwordx4 v[212:215], v145, s[4:5]
	global_load_dwordx4 v[216:219], v145, s[4:5] offset:256
	global_load_dwordx4 v[220:223], v145, s[4:5] offset:2048
	global_load_dwordx4 v[224:227], v145, s[4:5] offset:2304
	s_add_u32 s62, s4, 0x20000
	s_addc_u32 s63, s5, 0
	global_load_dwordx4 v[228:231], v145, s[62:63]
	global_load_dwordx4 v[232:235], v145, s[62:63] offset:256
	global_load_dwordx4 v[236:239], v145, s[62:63] offset:2048
	global_load_dwordx4 v[240:243], v145, s[62:63] offset:2304
	s_add_u32 s62, s4, 0x40000
	s_addc_u32 s63, s5, 0
	global_load_dwordx4 v[244:247], v145, s[62:63]
	global_load_dwordx4 v[178:181], v145, s[62:63] offset:256
	global_load_dwordx4 v[182:185], v145, s[62:63] offset:2048
	global_load_dwordx4 v[186:189], v145, s[62:63] offset:2304
	s_add_u32 s62, s4, 0x60000
	s_addc_u32 s63, s5, 0
	global_load_dwordx4 v[190:193], v145, s[62:63]
	global_load_dwordx4 v[162:165], v145, s[62:63] offset:256
	global_load_dwordx4 v[166:169], v145, s[62:63] offset:2048
	global_load_dwordx4 v[170:173], v145, s[62:63] offset:2304
	s_waitcnt vmcnt(12)
	v_lshlrev_b32_e32 v194, 16, v220
	v_lshlrev_b32_e32 v2, 16, v221
	v_and_b32_e32 v195, 0xffff0000, v220
	v_and_b32_e32 v3, 0xffff0000, v221
	v_rcp_f32_e32 v194, v194
	v_rcp_f32_e32 v2, v2
	v_rcp_f32_e32 v195, v195
	v_rcp_f32_e32 v3, v3
	v_lshlrev_b32_e32 v248, 16, v212
	v_lshlrev_b32_e32 v148, 16, v213
	v_and_b32_e32 v249, 0xffff0000, v212
	v_and_b32_e32 v149, 0xffff0000, v213
	v_pk_mul_f32 v[248:249], v[194:195], v[248:249]
	v_pk_mul_f32 v[148:149], v[2:3], v[148:149]
	v_pk_mul_f32 v[128:129], v[128:129], v[248:249]
	v_pk_mul_f32 v[130:131], v[130:131], v[148:149]
	v_lshlrev_b32_e32 v194, 16, v222
	v_lshlrev_b32_e32 v2, 16, v223
	v_and_b32_e32 v195, 0xffff0000, v222
	v_and_b32_e32 v3, 0xffff0000, v223
	v_rcp_f32_e32 v194, v194
	v_rcp_f32_e32 v2, v2
	v_rcp_f32_e32 v195, v195
	v_rcp_f32_e32 v3, v3
	v_lshlrev_b32_e32 v248, 16, v214
	v_lshlrev_b32_e32 v148, 16, v215
	v_and_b32_e32 v249, 0xffff0000, v214
	v_and_b32_e32 v149, 0xffff0000, v215
	v_pk_mul_f32 v[248:249], v[194:195], v[248:249]
	v_pk_mul_f32 v[148:149], v[2:3], v[148:149]
	v_pk_mul_f32 v[124:125], v[124:125], v[248:249]
	v_pk_mul_f32 v[126:127], v[126:127], v[148:149]
	v_lshlrev_b32_e32 v194, 16, v224
	v_lshlrev_b32_e32 v2, 16, v225
	v_and_b32_e32 v195, 0xffff0000, v224
	v_and_b32_e32 v3, 0xffff0000, v225
	v_rcp_f32_e32 v194, v194
	v_rcp_f32_e32 v2, v2
	v_rcp_f32_e32 v195, v195
	v_rcp_f32_e32 v3, v3
	v_lshlrev_b32_e32 v248, 16, v216
	v_lshlrev_b32_e32 v148, 16, v217
	v_and_b32_e32 v249, 0xffff0000, v216
	v_and_b32_e32 v149, 0xffff0000, v217
	v_pk_mul_f32 v[248:249], v[194:195], v[248:249]
	v_pk_mul_f32 v[148:149], v[2:3], v[148:149]
	v_pk_mul_f32 v[96:97], v[96:97], v[248:249]
	v_pk_mul_f32 v[98:99], v[98:99], v[148:149]
	v_lshlrev_b32_e32 v194, 16, v226
	v_lshlrev_b32_e32 v2, 16, v227
	v_and_b32_e32 v195, 0xffff0000, v226
	v_and_b32_e32 v3, 0xffff0000, v227
	v_rcp_f32_e32 v194, v194
	v_rcp_f32_e32 v2, v2
	v_rcp_f32_e32 v195, v195
	v_rcp_f32_e32 v3, v3
	v_lshlrev_b32_e32 v248, 16, v218
	v_lshlrev_b32_e32 v148, 16, v219
	v_and_b32_e32 v249, 0xffff0000, v218
	v_and_b32_e32 v149, 0xffff0000, v219
	v_pk_mul_f32 v[248:249], v[194:195], v[248:249]
	v_pk_mul_f32 v[148:149], v[2:3], v[148:149]
	v_pk_mul_f32 v[92:93], v[92:93], v[248:249]
	v_pk_mul_f32 v[94:95], v[94:95], v[148:149]
	s_add_u32 s62, s4, 0x100000
	s_addc_u32 s63, s5, 0
	global_load_dwordx4 v[212:215], v145, s[62:63]
	global_load_dwordx4 v[216:219], v145, s[62:63] offset:256
	global_load_dwordx4 v[220:223], v145, s[62:63] offset:2048
	global_load_dwordx4 v[224:227], v145, s[62:63] offset:2304
	s_waitcnt vmcnt(12)
	v_lshlrev_b32_e32 v194, 16, v236
	v_lshlrev_b32_e32 v2, 16, v237
	v_and_b32_e32 v195, 0xffff0000, v236
	v_and_b32_e32 v3, 0xffff0000, v237
	v_rcp_f32_e32 v194, v194
	v_rcp_f32_e32 v2, v2
	v_rcp_f32_e32 v195, v195
	v_rcp_f32_e32 v3, v3
	v_lshlrev_b32_e32 v248, 16, v228
	v_lshlrev_b32_e32 v148, 16, v229
	v_and_b32_e32 v249, 0xffff0000, v228
	v_and_b32_e32 v149, 0xffff0000, v229
	v_pk_mul_f32 v[248:249], v[194:195], v[248:249]
	v_pk_mul_f32 v[148:149], v[2:3], v[148:149]
	v_pk_mul_f32 v[120:121], v[120:121], v[248:249]
	v_pk_mul_f32 v[122:123], v[122:123], v[148:149]
	v_lshlrev_b32_e32 v194, 16, v238
	v_lshlrev_b32_e32 v2, 16, v239
	v_and_b32_e32 v195, 0xffff0000, v238
	v_and_b32_e32 v3, 0xffff0000, v239
	v_rcp_f32_e32 v194, v194
	v_rcp_f32_e32 v2, v2
	v_rcp_f32_e32 v195, v195
	v_rcp_f32_e32 v3, v3
	v_lshlrev_b32_e32 v248, 16, v230
	v_lshlrev_b32_e32 v148, 16, v231
	v_and_b32_e32 v249, 0xffff0000, v230
	v_and_b32_e32 v149, 0xffff0000, v231
	v_pk_mul_f32 v[248:249], v[194:195], v[248:249]
	v_pk_mul_f32 v[148:149], v[2:3], v[148:149]
	v_pk_mul_f32 v[116:117], v[116:117], v[248:249]
	v_pk_mul_f32 v[118:119], v[118:119], v[148:149]
	v_lshlrev_b32_e32 v194, 16, v240
	v_lshlrev_b32_e32 v2, 16, v241
	v_and_b32_e32 v195, 0xffff0000, v240
	v_and_b32_e32 v3, 0xffff0000, v241
	v_rcp_f32_e32 v194, v194
	v_rcp_f32_e32 v2, v2
	v_rcp_f32_e32 v195, v195
	v_rcp_f32_e32 v3, v3
	v_lshlrev_b32_e32 v248, 16, v232
	v_lshlrev_b32_e32 v148, 16, v233
	v_and_b32_e32 v249, 0xffff0000, v232
	v_and_b32_e32 v149, 0xffff0000, v233
	v_pk_mul_f32 v[248:249], v[194:195], v[248:249]
	v_pk_mul_f32 v[148:149], v[2:3], v[148:149]
	v_pk_mul_f32 v[88:89], v[88:89], v[248:249]
	v_pk_mul_f32 v[90:91], v[90:91], v[148:149]
	v_lshlrev_b32_e32 v194, 16, v242
	v_lshlrev_b32_e32 v2, 16, v243
	v_and_b32_e32 v195, 0xffff0000, v242
	v_and_b32_e32 v3, 0xffff0000, v243
	v_rcp_f32_e32 v194, v194
	v_rcp_f32_e32 v2, v2
	v_rcp_f32_e32 v195, v195
	v_rcp_f32_e32 v3, v3
	v_lshlrev_b32_e32 v248, 16, v234
	v_lshlrev_b32_e32 v148, 16, v235
	v_and_b32_e32 v249, 0xffff0000, v234
	v_and_b32_e32 v149, 0xffff0000, v235
	v_pk_mul_f32 v[248:249], v[194:195], v[248:249]
	v_pk_mul_f32 v[148:149], v[2:3], v[148:149]
	v_pk_mul_f32 v[84:85], v[84:85], v[248:249]
	v_pk_mul_f32 v[86:87], v[86:87], v[148:149]
	s_add_u32 s62, s4, 0x120000
	s_addc_u32 s63, s5, 0
	global_load_dwordx4 v[228:231], v145, s[62:63]
	global_load_dwordx4 v[232:235], v145, s[62:63] offset:256
	global_load_dwordx4 v[236:239], v145, s[62:63] offset:2048
	global_load_dwordx4 v[240:243], v145, s[62:63] offset:2304
	s_waitcnt vmcnt(12)
	v_lshlrev_b32_e32 v194, 16, v182
	v_lshlrev_b32_e32 v2, 16, v183
	v_and_b32_e32 v195, 0xffff0000, v182
	v_and_b32_e32 v3, 0xffff0000, v183
	v_rcp_f32_e32 v194, v194
	v_rcp_f32_e32 v2, v2
	v_rcp_f32_e32 v195, v195
	v_rcp_f32_e32 v3, v3
	v_lshlrev_b32_e32 v248, 16, v244
	v_lshlrev_b32_e32 v148, 16, v245
	v_and_b32_e32 v249, 0xffff0000, v244
	v_and_b32_e32 v149, 0xffff0000, v245
	v_pk_mul_f32 v[248:249], v[194:195], v[248:249]
	v_pk_mul_f32 v[148:149], v[2:3], v[148:149]
	v_pk_mul_f32 v[112:113], v[112:113], v[248:249]
	v_pk_mul_f32 v[114:115], v[114:115], v[148:149]
	v_lshlrev_b32_e32 v194, 16, v184
	v_lshlrev_b32_e32 v2, 16, v185
	v_and_b32_e32 v195, 0xffff0000, v184
	v_and_b32_e32 v3, 0xffff0000, v185
	v_rcp_f32_e32 v194, v194
	v_rcp_f32_e32 v2, v2
	v_rcp_f32_e32 v195, v195
	v_rcp_f32_e32 v3, v3
	v_lshlrev_b32_e32 v248, 16, v246
	v_lshlrev_b32_e32 v148, 16, v247
	v_and_b32_e32 v249, 0xffff0000, v246
	v_and_b32_e32 v149, 0xffff0000, v247
	v_pk_mul_f32 v[248:249], v[194:195], v[248:249]
	v_pk_mul_f32 v[148:149], v[2:3], v[148:149]
	v_pk_mul_f32 v[108:109], v[108:109], v[248:249]
	v_pk_mul_f32 v[110:111], v[110:111], v[148:149]
	v_lshlrev_b32_e32 v194, 16, v186
	v_lshlrev_b32_e32 v2, 16, v187
	v_and_b32_e32 v195, 0xffff0000, v186
	v_and_b32_e32 v3, 0xffff0000, v187
	v_rcp_f32_e32 v194, v194
	v_rcp_f32_e32 v2, v2
	v_rcp_f32_e32 v195, v195
	v_rcp_f32_e32 v3, v3
	v_lshlrev_b32_e32 v248, 16, v178
	v_lshlrev_b32_e32 v148, 16, v179
	v_and_b32_e32 v249, 0xffff0000, v178
	v_and_b32_e32 v149, 0xffff0000, v179
	v_pk_mul_f32 v[248:249], v[194:195], v[248:249]
	v_pk_mul_f32 v[148:149], v[2:3], v[148:149]
	v_pk_mul_f32 v[80:81], v[80:81], v[248:249]
	v_pk_mul_f32 v[82:83], v[82:83], v[148:149]
	v_lshlrev_b32_e32 v194, 16, v188
	v_lshlrev_b32_e32 v2, 16, v189
	v_and_b32_e32 v195, 0xffff0000, v188
	v_and_b32_e32 v3, 0xffff0000, v189
	v_rcp_f32_e32 v194, v194
	v_rcp_f32_e32 v2, v2
	v_rcp_f32_e32 v195, v195
	v_rcp_f32_e32 v3, v3
	v_lshlrev_b32_e32 v248, 16, v180
	v_lshlrev_b32_e32 v148, 16, v181
	v_and_b32_e32 v249, 0xffff0000, v180
	v_and_b32_e32 v149, 0xffff0000, v181
	v_pk_mul_f32 v[248:249], v[194:195], v[248:249]
	v_pk_mul_f32 v[148:149], v[2:3], v[148:149]
	v_pk_mul_f32 v[76:77], v[76:77], v[248:249]
	v_pk_mul_f32 v[78:79], v[78:79], v[148:149]
	s_add_u32 s62, s4, 0x140000
	s_addc_u32 s63, s5, 0
	global_load_dwordx4 v[244:247], v145, s[62:63]
	global_load_dwordx4 v[178:181], v145, s[62:63] offset:256
	global_load_dwordx4 v[182:185], v145, s[62:63] offset:2048
	global_load_dwordx4 v[186:189], v145, s[62:63] offset:2304
	s_waitcnt vmcnt(12)
	v_lshlrev_b32_e32 v194, 16, v166
	v_lshlrev_b32_e32 v2, 16, v167
	v_and_b32_e32 v195, 0xffff0000, v166
	v_and_b32_e32 v3, 0xffff0000, v167
	v_rcp_f32_e32 v194, v194
	v_rcp_f32_e32 v2, v2
	v_rcp_f32_e32 v195, v195
	v_rcp_f32_e32 v3, v3
	v_lshlrev_b32_e32 v248, 16, v190
	v_lshlrev_b32_e32 v148, 16, v191
	v_and_b32_e32 v249, 0xffff0000, v190
	v_and_b32_e32 v149, 0xffff0000, v191
	v_pk_mul_f32 v[248:249], v[194:195], v[248:249]
	v_pk_mul_f32 v[148:149], v[2:3], v[148:149]
	v_pk_mul_f32 v[104:105], v[104:105], v[248:249]
	v_pk_mul_f32 v[106:107], v[106:107], v[148:149]
	v_lshlrev_b32_e32 v194, 16, v168
	v_lshlrev_b32_e32 v2, 16, v169
	v_and_b32_e32 v195, 0xffff0000, v168
	v_and_b32_e32 v3, 0xffff0000, v169
	v_rcp_f32_e32 v194, v194
	v_rcp_f32_e32 v2, v2
	v_rcp_f32_e32 v195, v195
	v_rcp_f32_e32 v3, v3
	v_lshlrev_b32_e32 v248, 16, v192
	v_lshlrev_b32_e32 v148, 16, v193
	v_and_b32_e32 v249, 0xffff0000, v192
	v_and_b32_e32 v149, 0xffff0000, v193
	v_pk_mul_f32 v[248:249], v[194:195], v[248:249]
	v_pk_mul_f32 v[148:149], v[2:3], v[148:149]
	v_pk_mul_f32 v[100:101], v[100:101], v[248:249]
	v_pk_mul_f32 v[102:103], v[102:103], v[148:149]
	v_lshlrev_b32_e32 v194, 16, v170
	v_lshlrev_b32_e32 v2, 16, v171
	v_and_b32_e32 v195, 0xffff0000, v170
	v_and_b32_e32 v3, 0xffff0000, v171
	v_rcp_f32_e32 v194, v194
	v_rcp_f32_e32 v2, v2
	v_rcp_f32_e32 v195, v195
	v_rcp_f32_e32 v3, v3
	v_lshlrev_b32_e32 v248, 16, v162
	v_lshlrev_b32_e32 v148, 16, v163
	v_and_b32_e32 v249, 0xffff0000, v162
	v_and_b32_e32 v149, 0xffff0000, v163
	v_pk_mul_f32 v[248:249], v[194:195], v[248:249]
	v_pk_mul_f32 v[148:149], v[2:3], v[148:149]
	v_pk_mul_f32 v[72:73], v[72:73], v[248:249]
	v_pk_mul_f32 v[74:75], v[74:75], v[148:149]
	v_lshlrev_b32_e32 v194, 16, v172
	v_lshlrev_b32_e32 v2, 16, v173
	v_and_b32_e32 v195, 0xffff0000, v172
	v_and_b32_e32 v3, 0xffff0000, v173
	v_rcp_f32_e32 v194, v194
	v_rcp_f32_e32 v2, v2
	v_rcp_f32_e32 v195, v195
	v_rcp_f32_e32 v3, v3
	v_lshlrev_b32_e32 v248, 16, v164
	v_lshlrev_b32_e32 v148, 16, v165
	v_and_b32_e32 v249, 0xffff0000, v164
	v_and_b32_e32 v149, 0xffff0000, v165
	v_pk_mul_f32 v[248:249], v[194:195], v[248:249]
	v_pk_mul_f32 v[148:149], v[2:3], v[148:149]
	v_pk_mul_f32 v[68:69], v[68:69], v[248:249]
	v_pk_mul_f32 v[70:71], v[70:71], v[148:149]
	s_add_u32 s62, s4, 0x160000
	s_addc_u32 s63, s5, 0
	global_load_dwordx4 v[190:193], v145, s[62:63]
	global_load_dwordx4 v[162:165], v145, s[62:63] offset:256
	global_load_dwordx4 v[166:169], v145, s[62:63] offset:2048
	global_load_dwordx4 v[170:173], v145, s[62:63] offset:2304
	s_waitcnt vmcnt(12)
	v_lshlrev_b32_e32 v194, 16, v220
	v_lshlrev_b32_e32 v2, 16, v221
	v_and_b32_e32 v195, 0xffff0000, v220
	v_and_b32_e32 v3, 0xffff0000, v221
	v_rcp_f32_e32 v194, v194
	v_rcp_f32_e32 v2, v2
	v_rcp_f32_e32 v195, v195
	v_rcp_f32_e32 v3, v3
	v_lshlrev_b32_e32 v248, 16, v212
	v_lshlrev_b32_e32 v148, 16, v213
	v_and_b32_e32 v249, 0xffff0000, v212
	v_and_b32_e32 v149, 0xffff0000, v213
	v_pk_mul_f32 v[248:249], v[194:195], v[248:249]
	v_pk_mul_f32 v[148:149], v[2:3], v[148:149]
	v_pk_mul_f32 v[64:65], v[64:65], v[248:249]
	v_pk_mul_f32 v[66:67], v[66:67], v[148:149]
	v_lshlrev_b32_e32 v194, 16, v222
	v_lshlrev_b32_e32 v2, 16, v223
	v_and_b32_e32 v195, 0xffff0000, v222
	v_and_b32_e32 v3, 0xffff0000, v223
	v_rcp_f32_e32 v194, v194
	v_rcp_f32_e32 v2, v2
	v_rcp_f32_e32 v195, v195
	v_rcp_f32_e32 v3, v3
	v_lshlrev_b32_e32 v248, 16, v214
	v_lshlrev_b32_e32 v148, 16, v215
	v_and_b32_e32 v249, 0xffff0000, v214
	v_and_b32_e32 v149, 0xffff0000, v215
	v_pk_mul_f32 v[248:249], v[194:195], v[248:249]
	v_pk_mul_f32 v[148:149], v[2:3], v[148:149]
	v_pk_mul_f32 v[60:61], v[60:61], v[248:249]
	v_pk_mul_f32 v[62:63], v[62:63], v[148:149]
	v_lshlrev_b32_e32 v194, 16, v224
	v_lshlrev_b32_e32 v2, 16, v225
	v_and_b32_e32 v195, 0xffff0000, v224
	v_and_b32_e32 v3, 0xffff0000, v225
	v_rcp_f32_e32 v194, v194
	v_rcp_f32_e32 v2, v2
	v_rcp_f32_e32 v195, v195
	v_rcp_f32_e32 v3, v3
	v_lshlrev_b32_e32 v248, 16, v216
	v_lshlrev_b32_e32 v148, 16, v217
	v_and_b32_e32 v249, 0xffff0000, v216
	v_and_b32_e32 v149, 0xffff0000, v217
	v_pk_mul_f32 v[248:249], v[194:195], v[248:249]
	v_pk_mul_f32 v[148:149], v[2:3], v[148:149]
	v_pk_mul_f32 v[32:33], v[32:33], v[248:249]
	v_pk_mul_f32 v[34:35], v[34:35], v[148:149]
	v_lshlrev_b32_e32 v194, 16, v226
	v_lshlrev_b32_e32 v2, 16, v227
	v_and_b32_e32 v195, 0xffff0000, v226
	v_and_b32_e32 v3, 0xffff0000, v227
	v_rcp_f32_e32 v194, v194
	v_rcp_f32_e32 v2, v2
	v_rcp_f32_e32 v195, v195
	v_rcp_f32_e32 v3, v3
	v_lshlrev_b32_e32 v248, 16, v218
	v_lshlrev_b32_e32 v148, 16, v219
	v_and_b32_e32 v249, 0xffff0000, v218
	v_and_b32_e32 v149, 0xffff0000, v219
	v_pk_mul_f32 v[248:249], v[194:195], v[248:249]
	v_pk_mul_f32 v[148:149], v[2:3], v[148:149]
	v_pk_mul_f32 v[28:29], v[28:29], v[248:249]
	v_pk_mul_f32 v[30:31], v[30:31], v[148:149]
	s_waitcnt vmcnt(8)
	v_lshlrev_b32_e32 v194, 16, v236
	v_lshlrev_b32_e32 v2, 16, v237
	v_and_b32_e32 v195, 0xffff0000, v236
	v_and_b32_e32 v3, 0xffff0000, v237
	v_rcp_f32_e32 v194, v194
	v_rcp_f32_e32 v2, v2
	v_rcp_f32_e32 v195, v195
	v_rcp_f32_e32 v3, v3
	v_lshlrev_b32_e32 v248, 16, v228
	v_lshlrev_b32_e32 v148, 16, v229
	v_and_b32_e32 v249, 0xffff0000, v228
	v_and_b32_e32 v149, 0xffff0000, v229
	v_pk_mul_f32 v[248:249], v[194:195], v[248:249]
	v_pk_mul_f32 v[148:149], v[2:3], v[148:149]
	v_pk_mul_f32 v[56:57], v[56:57], v[248:249]
	v_pk_mul_f32 v[58:59], v[58:59], v[148:149]
	v_lshlrev_b32_e32 v194, 16, v238
	v_lshlrev_b32_e32 v2, 16, v239
	v_and_b32_e32 v195, 0xffff0000, v238
	v_and_b32_e32 v3, 0xffff0000, v239
	v_rcp_f32_e32 v194, v194
	v_rcp_f32_e32 v2, v2
	v_rcp_f32_e32 v195, v195
	v_rcp_f32_e32 v3, v3
	v_lshlrev_b32_e32 v248, 16, v230
	v_lshlrev_b32_e32 v148, 16, v231
	v_and_b32_e32 v249, 0xffff0000, v230
	v_and_b32_e32 v149, 0xffff0000, v231
	v_pk_mul_f32 v[248:249], v[194:195], v[248:249]
	v_pk_mul_f32 v[148:149], v[2:3], v[148:149]
	v_pk_mul_f32 v[52:53], v[52:53], v[248:249]
	v_pk_mul_f32 v[54:55], v[54:55], v[148:149]
	v_lshlrev_b32_e32 v194, 16, v240
	v_lshlrev_b32_e32 v2, 16, v241
	v_and_b32_e32 v195, 0xffff0000, v240
	v_and_b32_e32 v3, 0xffff0000, v241
	v_rcp_f32_e32 v194, v194
	v_rcp_f32_e32 v2, v2
	v_rcp_f32_e32 v195, v195
	v_rcp_f32_e32 v3, v3
	v_lshlrev_b32_e32 v248, 16, v232
	v_lshlrev_b32_e32 v148, 16, v233
	v_and_b32_e32 v249, 0xffff0000, v232
	v_and_b32_e32 v149, 0xffff0000, v233
	v_pk_mul_f32 v[248:249], v[194:195], v[248:249]
	v_pk_mul_f32 v[148:149], v[2:3], v[148:149]
	v_pk_mul_f32 v[24:25], v[24:25], v[248:249]
	v_pk_mul_f32 v[26:27], v[26:27], v[148:149]
	v_lshlrev_b32_e32 v194, 16, v242
	v_lshlrev_b32_e32 v2, 16, v243
	v_and_b32_e32 v195, 0xffff0000, v242
	v_and_b32_e32 v3, 0xffff0000, v243
	v_rcp_f32_e32 v194, v194
	v_rcp_f32_e32 v2, v2
	v_rcp_f32_e32 v195, v195
	v_rcp_f32_e32 v3, v3
	v_lshlrev_b32_e32 v248, 16, v234
	v_lshlrev_b32_e32 v148, 16, v235
	v_and_b32_e32 v249, 0xffff0000, v234
	v_and_b32_e32 v149, 0xffff0000, v235
	v_pk_mul_f32 v[248:249], v[194:195], v[248:249]
	v_pk_mul_f32 v[148:149], v[2:3], v[148:149]
	v_pk_mul_f32 v[20:21], v[20:21], v[248:249]
	v_pk_mul_f32 v[22:23], v[22:23], v[148:149]
	s_waitcnt vmcnt(4)
	v_lshlrev_b32_e32 v194, 16, v182
	v_lshlrev_b32_e32 v2, 16, v183
	v_and_b32_e32 v195, 0xffff0000, v182
	v_and_b32_e32 v3, 0xffff0000, v183
	v_rcp_f32_e32 v194, v194
	v_rcp_f32_e32 v2, v2
	v_rcp_f32_e32 v195, v195
	v_rcp_f32_e32 v3, v3
	v_lshlrev_b32_e32 v248, 16, v244
	v_lshlrev_b32_e32 v148, 16, v245
	v_and_b32_e32 v249, 0xffff0000, v244
	v_and_b32_e32 v149, 0xffff0000, v245
	v_pk_mul_f32 v[248:249], v[194:195], v[248:249]
	v_pk_mul_f32 v[148:149], v[2:3], v[148:149]
	v_pk_mul_f32 v[48:49], v[48:49], v[248:249]
	v_pk_mul_f32 v[50:51], v[50:51], v[148:149]
	v_lshlrev_b32_e32 v194, 16, v184
	v_lshlrev_b32_e32 v2, 16, v185
	v_and_b32_e32 v195, 0xffff0000, v184
	v_and_b32_e32 v3, 0xffff0000, v185
	v_rcp_f32_e32 v194, v194
	v_rcp_f32_e32 v2, v2
	v_rcp_f32_e32 v195, v195
	v_rcp_f32_e32 v3, v3
	v_lshlrev_b32_e32 v248, 16, v246
	v_lshlrev_b32_e32 v148, 16, v247
	v_and_b32_e32 v249, 0xffff0000, v246
	v_and_b32_e32 v149, 0xffff0000, v247
	v_pk_mul_f32 v[248:249], v[194:195], v[248:249]
	v_pk_mul_f32 v[148:149], v[2:3], v[148:149]
	v_pk_mul_f32 v[44:45], v[44:45], v[248:249]
	v_pk_mul_f32 v[46:47], v[46:47], v[148:149]
	v_lshlrev_b32_e32 v194, 16, v186
	v_lshlrev_b32_e32 v2, 16, v187
	v_and_b32_e32 v195, 0xffff0000, v186
	v_and_b32_e32 v3, 0xffff0000, v187
	v_rcp_f32_e32 v194, v194
	v_rcp_f32_e32 v2, v2
	v_rcp_f32_e32 v195, v195
	v_rcp_f32_e32 v3, v3
	v_lshlrev_b32_e32 v248, 16, v178
	v_lshlrev_b32_e32 v148, 16, v179
	v_and_b32_e32 v249, 0xffff0000, v178
	v_and_b32_e32 v149, 0xffff0000, v179
	v_pk_mul_f32 v[248:249], v[194:195], v[248:249]
	v_pk_mul_f32 v[148:149], v[2:3], v[148:149]
	v_pk_mul_f32 v[16:17], v[16:17], v[248:249]
	v_pk_mul_f32 v[18:19], v[18:19], v[148:149]
	v_lshlrev_b32_e32 v194, 16, v188
	v_lshlrev_b32_e32 v2, 16, v189
	v_and_b32_e32 v195, 0xffff0000, v188
	v_and_b32_e32 v3, 0xffff0000, v189
	v_rcp_f32_e32 v194, v194
	v_rcp_f32_e32 v2, v2
	v_rcp_f32_e32 v195, v195
	v_rcp_f32_e32 v3, v3
	v_lshlrev_b32_e32 v248, 16, v180
	v_lshlrev_b32_e32 v148, 16, v181
	v_and_b32_e32 v249, 0xffff0000, v180
	v_and_b32_e32 v149, 0xffff0000, v181
	v_pk_mul_f32 v[248:249], v[194:195], v[248:249]
	v_pk_mul_f32 v[148:149], v[2:3], v[148:149]
	v_pk_mul_f32 v[12:13], v[12:13], v[248:249]
	v_pk_mul_f32 v[14:15], v[14:15], v[148:149]
	s_waitcnt vmcnt(0)
	v_lshlrev_b32_e32 v194, 16, v166
	v_lshlrev_b32_e32 v2, 16, v167
	v_and_b32_e32 v195, 0xffff0000, v166
	v_and_b32_e32 v3, 0xffff0000, v167
	v_rcp_f32_e32 v194, v194
	v_rcp_f32_e32 v2, v2
	v_rcp_f32_e32 v195, v195
	v_rcp_f32_e32 v3, v3
	v_lshlrev_b32_e32 v248, 16, v190
	v_lshlrev_b32_e32 v148, 16, v191
	v_and_b32_e32 v249, 0xffff0000, v190
	v_and_b32_e32 v149, 0xffff0000, v191
	v_pk_mul_f32 v[248:249], v[194:195], v[248:249]
	v_pk_mul_f32 v[148:149], v[2:3], v[148:149]
	v_pk_mul_f32 v[40:41], v[40:41], v[248:249]
	v_pk_mul_f32 v[42:43], v[42:43], v[148:149]
	v_lshlrev_b32_e32 v194, 16, v168
	v_lshlrev_b32_e32 v2, 16, v169
	v_and_b32_e32 v195, 0xffff0000, v168
	v_and_b32_e32 v3, 0xffff0000, v169
	v_rcp_f32_e32 v194, v194
	v_rcp_f32_e32 v2, v2
	v_rcp_f32_e32 v195, v195
	v_rcp_f32_e32 v3, v3
	v_lshlrev_b32_e32 v248, 16, v192
	v_lshlrev_b32_e32 v148, 16, v193
	v_and_b32_e32 v249, 0xffff0000, v192
	v_and_b32_e32 v149, 0xffff0000, v193
	v_pk_mul_f32 v[248:249], v[194:195], v[248:249]
	v_pk_mul_f32 v[148:149], v[2:3], v[148:149]
	v_pk_mul_f32 v[36:37], v[36:37], v[248:249]
	v_pk_mul_f32 v[38:39], v[38:39], v[148:149]
	v_lshlrev_b32_e32 v194, 16, v170
	v_lshlrev_b32_e32 v2, 16, v171
	v_and_b32_e32 v195, 0xffff0000, v170
	v_and_b32_e32 v3, 0xffff0000, v171
	v_rcp_f32_e32 v194, v194
	v_rcp_f32_e32 v2, v2
	v_rcp_f32_e32 v195, v195
	v_rcp_f32_e32 v3, v3
	v_lshlrev_b32_e32 v248, 16, v162
	v_lshlrev_b32_e32 v148, 16, v163
	v_and_b32_e32 v249, 0xffff0000, v162
	v_and_b32_e32 v149, 0xffff0000, v163
	v_pk_mul_f32 v[248:249], v[194:195], v[248:249]
	v_pk_mul_f32 v[148:149], v[2:3], v[148:149]
	v_pk_mul_f32 v[8:9], v[8:9], v[248:249]
	v_pk_mul_f32 v[10:11], v[10:11], v[148:149]
	v_lshlrev_b32_e32 v194, 16, v172
	v_lshlrev_b32_e32 v2, 16, v173
	v_and_b32_e32 v195, 0xffff0000, v172
	v_and_b32_e32 v3, 0xffff0000, v173
	v_rcp_f32_e32 v194, v194
	v_rcp_f32_e32 v2, v2
	v_rcp_f32_e32 v195, v195
	v_rcp_f32_e32 v3, v3
	v_lshlrev_b32_e32 v248, 16, v164
	v_lshlrev_b32_e32 v148, 16, v165
	v_and_b32_e32 v249, 0xffff0000, v164
	v_and_b32_e32 v149, 0xffff0000, v165
	v_pk_mul_f32 v[248:249], v[194:195], v[248:249]
	v_pk_mul_f32 v[148:149], v[2:3], v[148:149]
	v_pk_mul_f32 v[4:5], v[4:5], v[248:249]
	v_pk_mul_f32 v[6:7], v[6:7], v[148:149]
	s_branch .Lem_done
.Lem_b3:
	global_load_dwordx4 v[212:215], v145, s[4:5]
	global_load_dwordx4 v[216:219], v145, s[4:5] offset:256
	s_add_u32 s62, s4, 0x20000
	s_addc_u32 s63, s5, 0
	global_load_dwordx4 v[220:223], v145, s[62:63]
	global_load_dwordx4 v[224:227], v145, s[62:63] offset:256
	s_add_u32 s62, s4, 0x40000
	s_addc_u32 s63, s5, 0
	global_load_dwordx4 v[228:231], v145, s[62:63]
	global_load_dwordx4 v[232:235], v145, s[62:63] offset:256
	s_add_u32 s62, s4, 0x60000
	s_addc_u32 s63, s5, 0
	global_load_dwordx4 v[236:239], v145, s[62:63]
	global_load_dwordx4 v[240:243], v145, s[62:63] offset:256
	s_add_u32 s62, s4, 0x100000
	s_addc_u32 s63, s5, 0
	global_load_dwordx4 v[244:247], v145, s[62:63]
	global_load_dwordx4 v[178:181], v145, s[62:63] offset:256
	s_add_u32 s62, s4, 0x120000
	s_addc_u32 s63, s5, 0
	global_load_dwordx4 v[182:185], v145, s[62:63]
	global_load_dwordx4 v[186:189], v145, s[62:63] offset:256
	s_add_u32 s62, s4, 0x140000
	s_addc_u32 s63, s5, 0
	global_load_dwordx4 v[190:193], v145, s[62:63]
	global_load_dwordx4 v[162:165], v145, s[62:63] offset:256
	s_add_u32 s62, s4, 0x160000
	s_addc_u32 s63, s5, 0
	global_load_dwordx4 v[166:169], v145, s[62:63]
	global_load_dwordx4 v[170:173], v145, s[62:63] offset:256
	s_waitcnt vmcnt(14)
	v_lshlrev_b32_e32 v194, 16, v212
	v_lshlrev_b32_e32 v248, 16, v213
	v_and_b32_e32 v195, 0xffff0000, v212
	v_and_b32_e32 v249, 0xffff0000, v213
	v_pk_mul_f32 v[128:129], v[128:129], v[194:195]
	v_pk_mul_f32 v[130:131], v[130:131], v[248:249]
	v_lshlrev_b32_e32 v194, 16, v214
	v_lshlrev_b32_e32 v248, 16, v215
	v_and_b32_e32 v195, 0xffff0000, v214
	v_and_b32_e32 v249, 0xffff0000, v215
	v_pk_mul_f32 v[124:125], v[124:125], v[194:195]
	v_pk_mul_f32 v[126:127], v[126:127], v[248:249]
	v_cvt_pk_bf16_f32 v212, v128, v129
	v_cvt_pk_bf16_f32 v213, v130, v131
	v_cvt_pk_bf16_f32 v214, v124, v125
	v_cvt_pk_bf16_f32 v215, v126, v127
	global_store_dwordx4 v148, v[212:215], s[30:31]
	v_lshlrev_b32_e32 v194, 16, v216
	v_lshlrev_b32_e32 v248, 16, v217
	v_and_b32_e32 v195, 0xffff0000, v216
	v_and_b32_e32 v249, 0xffff0000, v217
	v_pk_mul_f32 v[96:97], v[96:97], v[194:195]
	v_pk_mul_f32 v[98:99], v[98:99], v[248:249]
	v_lshlrev_b32_e32 v194, 16, v218
	v_lshlrev_b32_e32 v248, 16, v219
	v_and_b32_e32 v195, 0xffff0000, v218
	v_and_b32_e32 v249, 0xffff0000, v219
	v_pk_mul_f32 v[92:93], v[92:93], v[194:195]
	v_pk_mul_f32 v[94:95], v[94:95], v[248:249]
	v_cvt_pk_bf16_f32 v216, v96, v97
	v_cvt_pk_bf16_f32 v217, v98, v99
	v_cvt_pk_bf16_f32 v218, v92, v93
	v_cvt_pk_bf16_f32 v219, v94, v95
	global_store_dwordx4 v148, v[216:219], s[30:31] offset:256
	s_waitcnt vmcnt(14)
	s_add_u32 s62, s30, 0x8000
	s_addc_u32 s63, s31, 0
	v_lshlrev_b32_e32 v194, 16, v220
	v_lshlrev_b32_e32 v248, 16, v221
	v_and_b32_e32 v195, 0xffff0000, v220
	v_and_b32_e32 v249, 0xffff0000, v221
	v_pk_mul_f32 v[120:121], v[120:121], v[194:195]
	v_pk_mul_f32 v[122:123], v[122:123], v[248:249]
	v_lshlrev_b32_e32 v194, 16, v222
	v_lshlrev_b32_e32 v248, 16, v223
	v_and_b32_e32 v195, 0xffff0000, v222
	v_and_b32_e32 v249, 0xffff0000, v223
	v_pk_mul_f32 v[116:117], v[116:117], v[194:195]
	v_pk_mul_f32 v[118:119], v[118:119], v[248:249]
	v_cvt_pk_bf16_f32 v220, v120, v121
	v_cvt_pk_bf16_f32 v221, v122, v123
	v_cvt_pk_bf16_f32 v222, v116, v117
	v_cvt_pk_bf16_f32 v223, v118, v119
	global_store_dwordx4 v148, v[220:223], s[62:63]
	v_lshlrev_b32_e32 v194, 16, v224
	v_lshlrev_b32_e32 v248, 16, v225
	v_and_b32_e32 v195, 0xffff0000, v224
	v_and_b32_e32 v249, 0xffff0000, v225
	v_pk_mul_f32 v[88:89], v[88:89], v[194:195]
	v_pk_mul_f32 v[90:91], v[90:91], v[248:249]
	v_lshlrev_b32_e32 v194, 16, v226
	v_lshlrev_b32_e32 v248, 16, v227
	v_and_b32_e32 v195, 0xffff0000, v226
	v_and_b32_e32 v249, 0xffff0000, v227
	v_pk_mul_f32 v[84:85], v[84:85], v[194:195]
	v_pk_mul_f32 v[86:87], v[86:87], v[248:249]
	v_cvt_pk_bf16_f32 v224, v88, v89
	v_cvt_pk_bf16_f32 v225, v90, v91
	v_cvt_pk_bf16_f32 v226, v84, v85
	v_cvt_pk_bf16_f32 v227, v86, v87
	global_store_dwordx4 v148, v[224:227], s[62:63] offset:256
	s_waitcnt vmcnt(14)
	s_add_u32 s62, s30, 0x10000
	s_addc_u32 s63, s31, 0
	v_lshlrev_b32_e32 v194, 16, v228
	v_lshlrev_b32_e32 v248, 16, v229
	v_and_b32_e32 v195, 0xffff0000, v228
	v_and_b32_e32 v249, 0xffff0000, v229
	v_pk_mul_f32 v[112:113], v[112:113], v[194:195]
	v_pk_mul_f32 v[114:115], v[114:115], v[248:249]
	v_lshlrev_b32_e32 v194, 16, v230
	v_lshlrev_b32_e32 v248, 16, v231
	v_and_b32_e32 v195, 0xffff0000, v230
	v_and_b32_e32 v249, 0xffff0000, v231
	v_pk_mul_f32 v[108:109], v[108:109], v[194:195]
	v_pk_mul_f32 v[110:111], v[110:111], v[248:249]
	v_cvt_pk_bf16_f32 v228, v112, v113
	v_cvt_pk_bf16_f32 v229, v114, v115
	v_cvt_pk_bf16_f32 v230, v108, v109
	v_cvt_pk_bf16_f32 v231, v110, v111
	global_store_dwordx4 v148, v[228:231], s[62:63]
	v_lshlrev_b32_e32 v194, 16, v232
	v_lshlrev_b32_e32 v248, 16, v233
	v_and_b32_e32 v195, 0xffff0000, v232
	v_and_b32_e32 v249, 0xffff0000, v233
	v_pk_mul_f32 v[80:81], v[80:81], v[194:195]
	v_pk_mul_f32 v[82:83], v[82:83], v[248:249]
	v_lshlrev_b32_e32 v194, 16, v234
	v_lshlrev_b32_e32 v248, 16, v235
	v_and_b32_e32 v195, 0xffff0000, v234
	v_and_b32_e32 v249, 0xffff0000, v235
	v_pk_mul_f32 v[76:77], v[76:77], v[194:195]
	v_pk_mul_f32 v[78:79], v[78:79], v[248:249]
	v_cvt_pk_bf16_f32 v232, v80, v81
	v_cvt_pk_bf16_f32 v233, v82, v83
	v_cvt_pk_bf16_f32 v234, v76, v77
	v_cvt_pk_bf16_f32 v235, v78, v79
	global_store_dwordx4 v148, v[232:235], s[62:63] offset:256
	s_waitcnt vmcnt(14)
	s_add_u32 s62, s30, 0x18000
	s_addc_u32 s63, s31, 0
	v_lshlrev_b32_e32 v194, 16, v236
	v_lshlrev_b32_e32 v248, 16, v237
	v_and_b32_e32 v195, 0xffff0000, v236
	v_and_b32_e32 v249, 0xffff0000, v237
	v_pk_mul_f32 v[104:105], v[104:105], v[194:195]
	v_pk_mul_f32 v[106:107], v[106:107], v[248:249]
	v_lshlrev_b32_e32 v194, 16, v238
	v_lshlrev_b32_e32 v248, 16, v239
	v_and_b32_e32 v195, 0xffff0000, v238
	v_and_b32_e32 v249, 0xffff0000, v239
	v_pk_mul_f32 v[100:101], v[100:101], v[194:195]
	v_pk_mul_f32 v[102:103], v[102:103], v[248:249]
	v_cvt_pk_bf16_f32 v236, v104, v105
	v_cvt_pk_bf16_f32 v237, v106, v107
	v_cvt_pk_bf16_f32 v238, v100, v101
	v_cvt_pk_bf16_f32 v239, v102, v103
	global_store_dwordx4 v148, v[236:239], s[62:63]
	v_lshlrev_b32_e32 v194, 16, v240
	v_lshlrev_b32_e32 v248, 16, v241
	v_and_b32_e32 v195, 0xffff0000, v240
	v_and_b32_e32 v249, 0xffff0000, v241
	v_pk_mul_f32 v[72:73], v[72:73], v[194:195]
	v_pk_mul_f32 v[74:75], v[74:75], v[248:249]
	v_lshlrev_b32_e32 v194, 16, v242
	v_lshlrev_b32_e32 v248, 16, v243
	v_and_b32_e32 v195, 0xffff0000, v242
	v_and_b32_e32 v249, 0xffff0000, v243
	v_pk_mul_f32 v[68:69], v[68:69], v[194:195]
	v_pk_mul_f32 v[70:71], v[70:71], v[248:249]
	v_cvt_pk_bf16_f32 v240, v72, v73
	v_cvt_pk_bf16_f32 v241, v74, v75
	v_cvt_pk_bf16_f32 v242, v68, v69
	v_cvt_pk_bf16_f32 v243, v70, v71
	global_store_dwordx4 v148, v[240:243], s[62:63] offset:256
	s_waitcnt vmcnt(14)
	s_add_u32 s62, s30, 0x40000
	s_addc_u32 s63, s31, 0
	v_lshlrev_b32_e32 v194, 16, v244
	v_lshlrev_b32_e32 v248, 16, v245
	v_and_b32_e32 v195, 0xffff0000, v244
	v_and_b32_e32 v249, 0xffff0000, v245
	v_pk_mul_f32 v[64:65], v[64:65], v[194:195]
	v_pk_mul_f32 v[66:67], v[66:67], v[248:249]
	v_lshlrev_b32_e32 v194, 16, v246
	v_lshlrev_b32_e32 v248, 16, v247
	v_and_b32_e32 v195, 0xffff0000, v246
	v_and_b32_e32 v249, 0xffff0000, v247
	v_pk_mul_f32 v[60:61], v[60:61], v[194:195]
	v_pk_mul_f32 v[62:63], v[62:63], v[248:249]
	v_cvt_pk_bf16_f32 v244, v64, v65
	v_cvt_pk_bf16_f32 v245, v66, v67
	v_cvt_pk_bf16_f32 v246, v60, v61
	v_cvt_pk_bf16_f32 v247, v62, v63
	global_store_dwordx4 v148, v[244:247], s[62:63]
	v_lshlrev_b32_e32 v194, 16, v178
	v_lshlrev_b32_e32 v248, 16, v179
	v_and_b32_e32 v195, 0xffff0000, v178
	v_and_b32_e32 v249, 0xffff0000, v179
	v_pk_mul_f32 v[32:33], v[32:33], v[194:195]
	v_pk_mul_f32 v[34:35], v[34:35], v[248:249]
	v_lshlrev_b32_e32 v194, 16, v180
	v_lshlrev_b32_e32 v248, 16, v181
	v_and_b32_e32 v195, 0xffff0000, v180
	v_and_b32_e32 v249, 0xffff0000, v181
	v_pk_mul_f32 v[28:29], v[28:29], v[194:195]
	v_pk_mul_f32 v[30:31], v[30:31], v[248:249]
	v_cvt_pk_bf16_f32 v178, v32, v33
	v_cvt_pk_bf16_f32 v179, v34, v35
	v_cvt_pk_bf16_f32 v180, v28, v29
	v_cvt_pk_bf16_f32 v181, v30, v31
	global_store_dwordx4 v148, v[178:181], s[62:63] offset:256
	s_waitcnt vmcnt(14)
	s_add_u32 s62, s30, 0x48000
	s_addc_u32 s63, s31, 0
	v_lshlrev_b32_e32 v194, 16, v182
	v_lshlrev_b32_e32 v248, 16, v183
	v_and_b32_e32 v195, 0xffff0000, v182
	v_and_b32_e32 v249, 0xffff0000, v183
	v_pk_mul_f32 v[56:57], v[56:57], v[194:195]
	v_pk_mul_f32 v[58:59], v[58:59], v[248:249]
	v_lshlrev_b32_e32 v194, 16, v184
	v_lshlrev_b32_e32 v248, 16, v185
	v_and_b32_e32 v195, 0xffff0000, v184
	v_and_b32_e32 v249, 0xffff0000, v185
	v_pk_mul_f32 v[52:53], v[52:53], v[194:195]
	v_pk_mul_f32 v[54:55], v[54:55], v[248:249]
	v_cvt_pk_bf16_f32 v182, v56, v57
	v_cvt_pk_bf16_f32 v183, v58, v59
	v_cvt_pk_bf16_f32 v184, v52, v53
	v_cvt_pk_bf16_f32 v185, v54, v55
	global_store_dwordx4 v148, v[182:185], s[62:63]
	v_lshlrev_b32_e32 v194, 16, v186
	v_lshlrev_b32_e32 v248, 16, v187
	v_and_b32_e32 v195, 0xffff0000, v186
	v_and_b32_e32 v249, 0xffff0000, v187
	v_pk_mul_f32 v[24:25], v[24:25], v[194:195]
	v_pk_mul_f32 v[26:27], v[26:27], v[248:249]
	v_lshlrev_b32_e32 v194, 16, v188
	v_lshlrev_b32_e32 v248, 16, v189
	v_and_b32_e32 v195, 0xffff0000, v188
	v_and_b32_e32 v249, 0xffff0000, v189
	v_pk_mul_f32 v[20:21], v[20:21], v[194:195]
	v_pk_mul_f32 v[22:23], v[22:23], v[248:249]
	v_cvt_pk_bf16_f32 v186, v24, v25
	v_cvt_pk_bf16_f32 v187, v26, v27
	v_cvt_pk_bf16_f32 v188, v20, v21
	v_cvt_pk_bf16_f32 v189, v22, v23
	global_store_dwordx4 v148, v[186:189], s[62:63] offset:256
	s_waitcnt vmcnt(14)
	s_add_u32 s62, s30, 0x50000
	s_addc_u32 s63, s31, 0
	v_lshlrev_b32_e32 v194, 16, v190
	v_lshlrev_b32_e32 v248, 16, v191
	v_and_b32_e32 v195, 0xffff0000, v190
	v_and_b32_e32 v249, 0xffff0000, v191
	v_pk_mul_f32 v[48:49], v[48:49], v[194:195]
	v_pk_mul_f32 v[50:51], v[50:51], v[248:249]
	v_lshlrev_b32_e32 v194, 16, v192
	v_lshlrev_b32_e32 v248, 16, v193
	v_and_b32_e32 v195, 0xffff0000, v192
	v_and_b32_e32 v249, 0xffff0000, v193
	v_pk_mul_f32 v[44:45], v[44:45], v[194:195]
	v_pk_mul_f32 v[46:47], v[46:47], v[248:249]
	v_cvt_pk_bf16_f32 v190, v48, v49
	v_cvt_pk_bf16_f32 v191, v50, v51
	v_cvt_pk_bf16_f32 v192, v44, v45
	v_cvt_pk_bf16_f32 v193, v46, v47
	global_store_dwordx4 v148, v[190:193], s[62:63]
	v_lshlrev_b32_e32 v194, 16, v162
	v_lshlrev_b32_e32 v248, 16, v163
	v_and_b32_e32 v195, 0xffff0000, v162
	v_and_b32_e32 v249, 0xffff0000, v163
	v_pk_mul_f32 v[16:17], v[16:17], v[194:195]
	v_pk_mul_f32 v[18:19], v[18:19], v[248:249]
	v_lshlrev_b32_e32 v194, 16, v164
	v_lshlrev_b32_e32 v248, 16, v165
	v_and_b32_e32 v195, 0xffff0000, v164
	v_and_b32_e32 v249, 0xffff0000, v165
	v_pk_mul_f32 v[12:13], v[12:13], v[194:195]
	v_pk_mul_f32 v[14:15], v[14:15], v[248:249]
	v_cvt_pk_bf16_f32 v162, v16, v17
	v_cvt_pk_bf16_f32 v163, v18, v19
	v_cvt_pk_bf16_f32 v164, v12, v13
	v_cvt_pk_bf16_f32 v165, v14, v15
	global_store_dwordx4 v148, v[162:165], s[62:63] offset:256
	s_waitcnt vmcnt(14)
	s_add_u32 s62, s30, 0x58000
	s_addc_u32 s63, s31, 0
	v_lshlrev_b32_e32 v194, 16, v166
	v_lshlrev_b32_e32 v248, 16, v167
	v_and_b32_e32 v195, 0xffff0000, v166
	v_and_b32_e32 v249, 0xffff0000, v167
	v_pk_mul_f32 v[40:41], v[40:41], v[194:195]
	v_pk_mul_f32 v[42:43], v[42:43], v[248:249]
	v_lshlrev_b32_e32 v194, 16, v168
	v_lshlrev_b32_e32 v248, 16, v169
	v_and_b32_e32 v195, 0xffff0000, v168
	v_and_b32_e32 v249, 0xffff0000, v169
	v_pk_mul_f32 v[36:37], v[36:37], v[194:195]
	v_pk_mul_f32 v[38:39], v[38:39], v[248:249]
	v_cvt_pk_bf16_f32 v166, v40, v41
	v_cvt_pk_bf16_f32 v167, v42, v43
	v_cvt_pk_bf16_f32 v168, v36, v37
	v_cvt_pk_bf16_f32 v169, v38, v39
	global_store_dwordx4 v148, v[166:169], s[62:63]
	v_lshlrev_b32_e32 v194, 16, v170
	v_lshlrev_b32_e32 v248, 16, v171
	v_and_b32_e32 v195, 0xffff0000, v170
	v_and_b32_e32 v249, 0xffff0000, v171
	v_pk_mul_f32 v[8:9], v[8:9], v[194:195]
	v_pk_mul_f32 v[10:11], v[10:11], v[248:249]
	v_lshlrev_b32_e32 v194, 16, v172
	v_lshlrev_b32_e32 v248, 16, v173
	v_and_b32_e32 v195, 0xffff0000, v172
	v_and_b32_e32 v249, 0xffff0000, v173
	v_pk_mul_f32 v[4:5], v[4:5], v[194:195]
	v_pk_mul_f32 v[6:7], v[6:7], v[248:249]
	v_cvt_pk_bf16_f32 v170, v8, v9
	v_cvt_pk_bf16_f32 v171, v10, v11
	v_cvt_pk_bf16_f32 v172, v4, v5
	v_cvt_pk_bf16_f32 v173, v6, v7
	global_store_dwordx4 v148, v[170:173], s[62:63] offset:256
.Lem_done:
.LBB0_672:
	s_andn2_b64 vcc, exec, s[40:41]
	s_mov_b64 s[2:3], -1
	s_cbranch_vccnz .LBB0_596
	s_cmp_lg_u32 s48, 0
	s_cbranch_scc0 .LBB0_675
	s_andn2_b64 vcc, exec, s[0:1]
	s_cbranch_vccnz .LBB0_595
	s_branch .LBB0_676
